# ml_prep: gate-chain max-plus scan by DPP prefix sum/max instead of 13 bpermute round trips; chain blocks hand their conv rounds to blocks 64..81
# speedup vs baseline: 1.2071x; 1.0040x over previous
.LBB0_691:
	s_add_i32 s17, s25, 0xffffff00
	s_cmp_lt_u32 s16, 4
	s_cselect_b32 s17, s25, s17
	v_or_b32_e32 v6, s17, v21
	s_cselect_b32 s17, 0xff, s72
	v_sub_u32_e32 v16, s17, v6
	s_cselect_b32 s26, 0x4000, 0
	v_cndmask_b32_e64 v6, v16, v6, s[14:15]
	v_add_u32_e32 v6, s26, v6
	s_add_i32 s26, s16, 1
	s_add_i32 s17, s16, -3
	s_cmp_lt_u32 s16, 3
	s_cselect_b32 s16, s26, s17
	v_lshl_or_b32 v16, s16, 6, v21
	s_cselect_b32 s16, 0xff, s72
	s_waitcnt vmcnt(1)
	v_mov_b32_e32 v15, v23
	v_sub_u32_e32 v20, s16, v16
	s_cselect_b32 s17, 0x4000, 0
	v_cndmask_b32_e64 v16, v20, v16, s[14:15]
	v_add_f32_e32 v15, v22, v15
	v_add_u32_e32 v26, s17, v16
	v_min_f32_e32 v16, 0, v15
	v_mul_f32_e64 v15, |v15|, s73
	v_exp_f32_e32 v15, v15
	v_ashrrev_i32_e32 v27, 31, v26
	v_lshlrev_b64 v[26:27], 6, v[26:27]
	v_lshl_add_u64 v[26:27], s[22:23], 0, v[26:27]
	v_lshl_add_u64 v[28:29], v[4:5], 2, v[26:27]
	v_lshl_add_u64 v[26:27], v[2:3], 2, v[26:27]
	v_add_f32_e32 v25, 1.0, v15
	global_load_dword v23, v[28:29], off offset:32
	global_load_dword v20, v[26:27], off
	v_add_f32_e32 v26, -1.0, v25
	v_sub_f32_e32 v27, v26, v25
	v_add_f32_e32 v27, 1.0, v27
	v_sub_f32_e32 v26, v15, v26
	v_add_f32_e32 v28, v26, v27
	v_frexp_mant_f32_e32 v26, v25
	v_cmp_gt_f32_e64 s[16:17], s46, v26
	v_cvt_f64_f32_e32 v[26:27], v25
	v_frexp_exp_i32_f64_e32 v26, v[26:27]
	v_subbrev_co_u32_e64 v34, s[16:17], 0, v26, s[16:17]
	v_sub_u32_e32 v26, 0, v34
	v_ldexp_f32 v25, v25, v26
	v_ldexp_f32 v26, v28, v26
	v_add_f32_e32 v28, -1.0, v25
	v_add_f32_e32 v27, 1.0, v28
	v_sub_f32_e32 v27, v25, v27
	v_add_f32_e32 v29, v26, v27
	v_add_f32_e32 v27, 1.0, v25
	v_add_f32_e32 v30, -1.0, v27
	v_sub_f32_e32 v25, v25, v30
	v_add_f32_e32 v25, v26, v25
	v_add_f32_e32 v35, v27, v25
	v_rcp_f32_e32 v36, v35
	v_sub_f32_e32 v26, v35, v27
	v_add_f32_e32 v27, v28, v29
	v_sub_f32_e32 v25, v25, v26
	v_mul_f32_e32 v38, v27, v36
	v_sub_f32_e32 v26, v27, v28
	v_mul_f32_e32 v28, v35, v38
	v_fma_f32 v30, v38, v35, -v28
	v_fmac_f32_e32 v30, v38, v25
	v_sub_f32_e32 v37, v29, v26
	v_add_f32_e32 v26, v28, v30
	v_sub_f32_e32 v29, v27, v26
	v_pk_add_f32 v[32:33], v[26:27], v[28:29] neg_lo:[0,1] neg_hi:[0,1]
	v_mov_b32_e32 v31, v26
	v_pk_add_f32 v[26:27], v[32:33], v[30:31] neg_lo:[0,1] neg_hi:[0,1]
	v_cmp_neq_f32_e64 s[16:17], s0, v15
	v_add_f32_e32 v27, v37, v27
	v_add_f32_e32 v26, v26, v27
	v_add_f32_e32 v27, v29, v26
	v_mul_f32_e32 v37, v36, v27
	v_mul_f32_e32 v28, v35, v37
	v_fma_f32 v30, v37, v35, -v28
	v_fmac_f32_e32 v30, v37, v25
	v_sub_f32_e32 v25, v29, v27
	v_add_f32_e32 v25, v26, v25
	v_add_f32_e32 v26, v28, v30
	v_sub_f32_e32 v29, v27, v26
	v_pk_add_f32 v[32:33], v[26:27], v[28:29] neg_lo:[0,1] neg_hi:[0,1]
	v_mov_b32_e32 v31, v26
	v_pk_add_f32 v[26:27], v[32:33], v[30:31] neg_lo:[0,1] neg_hi:[0,1]
	s_add_i32 s25, s25, 64
	v_add_f32_e32 v25, v25, v27
	v_add_f32_e32 v25, v26, v25
	v_add_f32_e32 v27, v38, v37
	v_add_f32_e32 v25, v29, v25
	v_sub_f32_e32 v26, v27, v38
	v_mul_f32_e32 v25, v36, v25
	v_sub_f32_e32 v26, v37, v26
	v_add_f32_e32 v25, v26, v25
	v_add_f32_e32 v28, v27, v25
	v_mul_f32_e32 v30, v28, v28
	v_fmamk_f32 v26, v30, 0x3e9b6dac, v210
	v_fmaak_f32 v121, v30, v26, 0x3f2aaada
	v_cvt_f32_i32_e32 v26, v34
	v_sub_f32_e32 v27, v28, v27
	v_sub_f32_e32 v25, v25, v27
	v_mul_f32_e32 v27, v28, v30
	v_pk_mul_f32 v[30:31], v[26:27], v[120:121]
	v_ldexp_f32 v29, v28, 1
	v_fma_f32 v28, v26, s1, -v30
	v_fmac_f32_e32 v28, 0xb102e308, v26
	v_pk_add_f32 v[26:27], v[30:31], v[28:29]
	v_ldexp_f32 v25, v25, 1
	v_sub_f32_e32 v29, v27, v29
	v_sub_f32_e32 v29, v31, v29
	v_add_f32_e32 v33, v25, v29
	v_mov_b32_e32 v32, v30
	v_pk_add_f32 v[30:31], v[26:27], v[30:31] neg_lo:[0,1] neg_hi:[0,1]
	v_pk_add_f32 v[34:35], v[26:27], v[32:33]
	v_mov_b32_e32 v29, v26
	v_mov_b32_e32 v31, v35
	v_pk_add_f32 v[36:37], v[28:29], v[30:31] neg_lo:[0,1] neg_hi:[0,1]
	v_pk_add_f32 v[28:29], v[28:29], v[30:31]
	v_mov_b32_e32 v32, v33
	v_pk_add_f32 v[30:31], v[28:29], v[26:27] op_sel:[1,0] op_sel_hi:[0,1] neg_lo:[0,1] neg_hi:[0,1]
	v_pk_add_f32 v[38:39], v[34:35], v[30:31] op_sel_hi:[1,0] neg_lo:[0,1] neg_hi:[0,1]
	v_mov_b32_e32 v34, v35
	v_mov_b32_e32 v35, v29
	v_pk_mov_b32 v[30:31], v[26:27], v[30:31] op_sel:[1,0]
	v_mov_b32_e32 v33, v26
	v_pk_add_f32 v[30:31], v[34:35], v[30:31] neg_lo:[0,1] neg_hi:[0,1]
	v_mov_b32_e32 v38, v36
	v_pk_add_f32 v[26:27], v[32:33], v[30:31] neg_lo:[0,1] neg_hi:[0,1]
	v_mov_b32_e32 v37, v29
	v_pk_add_f32 v[30:31], v[38:39], v[26:27]
	s_cmpk_lg_i32 s26, 0x104
	v_pk_add_f32 v[32:33], v[30:31], v[30:31] op_sel:[0,1] op_sel_hi:[1,0]
	s_nop 0
	v_pk_add_f32 v[28:29], v[28:29], v[32:33] op_sel:[1,0] op_sel_hi:[0,1]
	v_mov_b32_e32 v31, v28
	v_pk_add_f32 v[34:35], v[30:31], v[36:37] neg_lo:[0,1] neg_hi:[0,1]
	v_mov_b32_e32 v27, v32
	v_sub_f32_e32 v25, v30, v34
	v_pk_add_f32 v[26:27], v[26:27], v[34:35] neg_lo:[0,1] neg_hi:[0,1]
	v_sub_f32_e32 v25, v36, v25
	v_add_f32_e32 v25, v26, v25
	v_add_f32_e32 v25, v25, v27
	v_add_f32_e32 v25, v28, v25
	v_cndmask_b32_e64 v25, v224, v25, s[16:17]
	v_cmp_ngt_f32_e64 s[16:17], -1.0, v15
	s_waitcnt vmcnt(2)
	v_add_f32_e32 v31, v12, v14
	v_cndmask_b32_e64 v25, v225, v25, s[16:17]
	v_cmp_neq_f32_e64 s[16:17], -1.0, v15
	s_nop 1
	v_cndmask_b32_e64 v25, v226, v25, s[16:17]
	v_cmp_lt_f32_e64 s[16:17], |v15|, s56
	s_nop 1
	v_cndmask_b32_e64 v15, v25, v15, s[16:17]
	v_sub_f32_e32 v15, v16, v15
	s_mov_b32 s16, s26
	v_mov_b32_e32 v26, v15
	s_nop 1
	v_add_f32_dpp v26, v26, v26 row_shr:1 row_mask:0xf bank_mask:0xf bound_ctrl:1
	s_nop 1
	v_add_f32_dpp v26, v26, v26 row_shr:2 row_mask:0xf bank_mask:0xf bound_ctrl:1
	s_nop 1
	v_add_f32_dpp v26, v26, v26 row_shr:4 row_mask:0xf bank_mask:0xf bound_ctrl:1
	s_nop 1
	v_add_f32_dpp v26, v26, v26 row_shr:8 row_mask:0xf bank_mask:0xf bound_ctrl:1
	s_nop 1
	v_add_f32_dpp v26, v26, v26 row_bcast:15 row_mask:0xa bank_mask:0xf
	s_nop 1
	v_add_f32_dpp v26, v26, v26 row_bcast:31 row_mask:0xc bank_mask:0xf
	v_sub_f32_e32 v27, v31, v26
	s_nop 1
	v_max_f32_dpp v27, v27, v27 row_shr:1 row_mask:0xf bank_mask:0xf
	s_nop 1
	v_max_f32_dpp v27, v27, v27 row_shr:2 row_mask:0xf bank_mask:0xf
	s_nop 1
	v_max_f32_dpp v27, v27, v27 row_shr:4 row_mask:0xf bank_mask:0xf
	s_nop 1
	v_max_f32_dpp v27, v27, v27 row_shr:8 row_mask:0xf bank_mask:0xf
	s_nop 1
	v_max_f32_dpp v27, v27, v27 row_bcast:15 row_mask:0xa bank_mask:0xf
	s_nop 1
	v_max_f32_dpp v27, v27, v27 row_bcast:31 row_mask:0xc bank_mask:0xf
	v_max_f32_e32 v27, v7, v27
	v_add_f32_e32 v26, v26, v27
	v_mov_b32_e32 v14, v7
	s_nop 0
	v_mov_b32_dpp v14, v26 wave_shr:1 row_mask:0xf bank_mask:0xf
	v_readlane_b32 vcc_lo, v26, 63
	v_mul_f32_e32 v27, 0xbfb8aa3b, v26
	v_exp_f32_e32 v16, v27
	v_add_f32_e32 v30, v14, v15
	v_ashrrev_i32_e32 v7, 31, v6
	v_pk_add_f32 v[14:15], v[30:31], v[26:27] op_sel_hi:[1,0] neg_lo:[0,1] neg_hi:[0,1]
	v_lshl_add_u64 v[6:7], v[6:7], 4, v[0:1]
	global_store_dwordx4 v[6:7], v[14:17], off
	v_mov_b32_e32 v7, vcc_lo
	s_waitcnt vmcnt(1)
	v_mov_b32_e32 v14, v20
	s_cbranch_scc1 .LBB0_691
	s_branch .LBB0_693
.LBB0_693:
	v_lshl_add_u32 v114, s24, 8, v8
	s_cmp_lt_u32 s24, 2
	s_cselect_b32 s4, 0x104000, 0
	s_cmp_eq_u32 s90, 0x200000
	s_cselect_b32 s4, 0, s4
	v_add_u32_e32 v114, s4, v114
	s_mov_b32 s4, 0x104000
	v_cmp_gt_i32_e32 vcc, s4, v114
	s_and_saveexec_b64 s[4:5], vcc
	s_cbranch_execz .LBB0_712
	s_load_dwordx4 s[12:15], s[18:19], 0xe0
	s_waitcnt lgkmcnt(0)
	s_add_u32 s6, s20, 0x6aa8000
	s_addc_u32 s7, s21, 0
	s_add_u32 s8, s20, 0x928000
	v_readlane_b32 s16, v255, 18
	s_addc_u32 s9, s21, 0
	s_mul_i32 s10, s16, 0xa000
	s_add_u32 s10, s12, s10
	s_addc_u32 s11, s13, 0
	s_lshl_b32 s12, s16, 13
	s_add_u32 s12, s14, s12
	v_lshlrev_b32_e32 v0, 3, v8
	s_addc_u32 s13, s15, 0
	v_lshl_add_u32 v115, s24, 11, v0
	s_mov_b64 s[14:15], 0
	s_branch .LBB0_696

.LBB0_712:
	s_or_b64 exec, exec, s[4:5]
	s_cmp_eq_u32 s90, 0x200000
	s_cbranch_scc1 .Lmp_done
	s_sub_i32 s6, s24, 64
	s_cmp_lt_u32 s6, 18
	s_cbranch_scc0 .Lmp_end
	s_cmp_ge_u32 s6, 9
	s_cselect_b32 s7, 1, 0
	s_cselect_b32 s8, 9, 0
	s_sub_i32 s6, s6, s8
	s_lshl_b32 s6, s6, 9
	s_add_i32 s24, s6, s7
	s_mov_b32 s90, 0x200000
	s_mov_b32 s91, 0x1000000
	v_mov_b32_e32 v8, v119
	s_branch .LBB0_693
.Lmp_done:
	v_readlane_b32 s90, v255, 13
	v_readlane_b32 s91, v255, 14
	s_mov_b32 s24, s2
.Lmp_end:
.LBB0_713:
	s_mov_b64 s[4:5], -1
	v_readlane_b32 s59, v255, 16
